# attention K/V staging straight-line: wave 0 issues its second task's loads together with the first (one global round trip per item less)
# baseline (speedup 1.0000x reference)
.LBB0_396:
	v_mov_b32_e32 v1, v197
	s_movk_i32 s0, 0x21f
	s_waitcnt vmcnt(0)
	v_readfirstlane_b32 s22, v1
	v_cmp_lt_i32_e32 vcc, s0, v1
	s_barrier
	s_and_saveexec_b64 s[0:1], vcc
	s_xor_b64 s[0:1], exec, s[0:1]
	s_lshl_b32 s23, s20, 12
	s_add_i32 s24, s23, -16
	s_or_saveexec_b64 s[0:1], s[0:1]
	s_and_b32 s23, s80, 3
	s_lshl_b32 s70, s21, 7
	v_mov_b32_e32 v53, s24
	s_xor_b64 exec, exec, s[0:1]
	s_cbranch_execz .LBB0_410
	v_and_b32_e32 v2, 7, v1
	s_lshl_b32 s24, s20, 12
	v_lshl_add_u32 v36, v2, 4, 0
	s_movk_i32 s27, 0x1170
	s_add_i32 s25, s70, 0xffffff80
	s_add_i32 s24, s24, -16
	s_lshl_b32 s26, s23, 6
	v_lshlrev_b32_e32 v0, 3, v2
	v_mad_u32_u24 v37, v2, s27, v36
	s_mov_b64 s[38:39], exec
	v_mov_b32_e32 v38, v1
	v_ashrrev_i32_e32 v21, 1, v38
	v_and_b32_e32 v39, -4, v21
	v_mov_b32_e32 v2, s25
	v_cmp_gt_i32_e32 vcc, s35, v39
	v_mov_b32_e32 v4, 0
	v_mov_b32_e32 v8, 0
	v_cndmask_b32_e32 v2, v233, v2, vcc
	v_add_u32_e32 v5, v2, v39
	v_cmp_gt_u32_e32 vcc, s79, v5
	v_lshlrev_b32_e32 v2, 1, v0
	v_mov_b32_e32 v9, 0
	v_mov_b32_e32 v10, 0
	v_mov_b32_e32 v11, 0
	v_mov_b32_e32 v12, 0
	v_mov_b32_e32 v13, 0
	v_mov_b32_e32 v14, 0
	v_mov_b32_e32 v15, 0
	s_and_saveexec_b64 s[40:41], vcc
	s_cbranch_execz .Lkv1_403
	v_or_b32_e32 v6, 0x8000, v5
	v_add_u32_e32 v7, s24, v5
	v_cmp_gt_u32_e32 vcc, 16, v5
	s_lshl_b32 s72, s26, 1
	s_nop 0
	v_cndmask_b32_e32 v5, v7, v6, vcc
	v_mov_b64_e32 v[6:7], s[96:97]
	v_mad_i64_i32 v[6:7], s[30:31], v5, s29, v[6:7]
	v_lshl_add_u64 v[6:7], v[6:7], 0, s[72:73]
	v_lshl_add_u64 v[6:7], v[6:7], 0, v[2:3]
	v_add_co_u32_e32 v6, vcc, 0x3000, v6
	s_nop 1
	v_addc_co_u32_e32 v7, vcc, 0, v7, vcc
	global_load_dwordx4 v[12:15], v[6:7], off
	global_load_dwordx4 v[8:11], v[6:7], off offset:512

.Lkv1_end:
	s_or_b64 exec, exec, s[40:41]
	s_cmp_gt_u32 s22, 63
	s_cbranch_scc1 .Lkv_other
	v_cmp_gt_u32_e32 vcc, 32, v38
	s_and_b64 exec, s[38:39], vcc
	v_add_u32_e32 v94, 0x200, v38
	v_mov_b32_e32 v59, 0
	v_ashrrev_i32_e32 v77, 1, v94
	v_and_b32_e32 v95, -4, v77
	v_mov_b32_e32 v58, s25
	v_cmp_gt_i32_e32 vcc, s35, v95
	v_mov_b32_e32 v60, 0
	v_mov_b32_e32 v64, 0
	v_cndmask_b32_e32 v58, v233, v58, vcc
	v_add_u32_e32 v61, v58, v95
	v_cmp_gt_u32_e32 vcc, s79, v61
	v_lshlrev_b32_e32 v58, 1, v0
	v_mov_b32_e32 v65, 0
	v_mov_b32_e32 v66, 0
	v_mov_b32_e32 v67, 0
	v_mov_b32_e32 v68, 0
	v_mov_b32_e32 v69, 0
	v_mov_b32_e32 v70, 0
	v_mov_b32_e32 v71, 0
	s_and_saveexec_b64 s[40:41], vcc
	s_cbranch_execz .Lkv2_403
	v_or_b32_e32 v62, 0x8000, v61
	v_add_u32_e32 v63, s24, v61
	v_cmp_gt_u32_e32 vcc, 16, v61
	s_lshl_b32 s72, s26, 1
	s_nop 0
	v_cndmask_b32_e32 v61, v63, v62, vcc
	v_mov_b64_e32 v[62:63], s[96:97]
	v_mad_i64_i32 v[62:63], s[30:31], v61, s29, v[62:63]
	v_lshl_add_u64 v[62:63], v[62:63], 0, s[72:73]
	v_lshl_add_u64 v[62:63], v[62:63], 0, v[58:59]
	v_add_co_u32_e32 v62, vcc, 0x3000, v62
	s_nop 1
	v_addc_co_u32_e32 v63, vcc, 0, v63, vcc
	global_load_dwordx4 v[68:71], v[62:63], off
	global_load_dwordx4 v[64:67], v[62:63], off offset:512
.Lkv2_403:
	s_or_b64 exec, exec, s[40:41]
	v_or_b32_e32 v61, 1, v95
	v_mov_b32_e32 v62, s25
	v_cmp_gt_i32_e32 vcc, s35, v61
	v_mov_b32_e32 v63, 0
	v_mov_b32_e32 v72, 0
	v_cndmask_b32_e32 v62, v233, v62, vcc
	v_add_u32_e32 v76, v62, v61
	v_cmp_gt_u32_e32 vcc, s79, v76
	v_mov_b32_e32 v61, 0
	v_mov_b32_e32 v62, 0
	v_mov_b32_e32 v73, 0
	v_mov_b32_e32 v74, 0
	v_mov_b32_e32 v75, 0
	s_and_saveexec_b64 s[40:41], vcc
	s_cbranch_execz .Lkv2_405
	v_or_b32_e32 v60, 0x8000, v76
	v_add_u32_e32 v61, s24, v76
	v_cmp_gt_u32_e32 vcc, 16, v76
	s_lshl_b32 s72, s26, 1
	s_nop 0
	v_cndmask_b32_e32 v62, v61, v60, vcc
	v_mov_b64_e32 v[60:61], s[96:97]
	v_mad_i64_i32 v[60:61], s[30:31], v62, s29, v[60:61]
	v_lshl_add_u64 v[60:61], v[60:61], 0, s[72:73]
	v_lshl_add_u64 v[60:61], v[60:61], 0, v[58:59]
	v_add_co_u32_e32 v60, vcc, 0x3000, v60
	s_nop 1
	v_addc_co_u32_e32 v61, vcc, 0, v61, vcc
	global_load_dwordx4 v[72:75], v[60:61], off
	s_nop 0
	global_load_dwordx4 v[60:63], v[60:61], off offset:512
.Lkv2_405:
	s_or_b64 exec, exec, s[40:41]
	v_or_b32_e32 v76, 2, v95
	v_mov_b32_e32 v78, s25
	v_cmp_gt_i32_e32 vcc, s35, v76
	v_mov_b32_e32 v80, 0
	v_mov_b32_e32 v81, 0
	v_cndmask_b32_e32 v78, v233, v78, vcc
	v_add_u32_e32 v78, v78, v76
	v_cmp_gt_u32_e32 vcc, s79, v78
	v_mov_b32_e32 v76, 0
	v_mov_b32_e32 v82, 0
	v_mov_b32_e32 v83, 0
	v_mov_b32_e32 v84, 0
	v_mov_b32_e32 v85, 0
	v_mov_b32_e32 v86, 0
	v_mov_b32_e32 v87, 0
	s_and_saveexec_b64 s[40:41], vcc
	s_cbranch_execz .Lkv2_407
	v_or_b32_e32 v79, 0x8000, v78
	v_add_u32_e32 v80, s24, v78
	v_cmp_gt_u32_e32 vcc, 16, v78
	s_lshl_b32 s72, s26, 1
	s_nop 0
	v_cndmask_b32_e32 v80, v80, v79, vcc
	v_mov_b64_e32 v[78:79], s[96:97]
	v_mad_i64_i32 v[78:79], s[30:31], v80, s29, v[78:79]
	v_lshl_add_u64 v[78:79], v[78:79], 0, s[72:73]
	v_lshl_add_u64 v[78:79], v[78:79], 0, v[58:59]
	v_add_co_u32_e32 v78, vcc, 0x3000, v78
	s_nop 1
	v_addc_co_u32_e32 v79, vcc, 0, v79, vcc
	global_load_dwordx4 v[84:87], v[78:79], off
	global_load_dwordx4 v[80:83], v[78:79], off offset:512
.Lkv2_407:
	s_or_b64 exec, exec, s[40:41]
	v_or_b32_e32 v96, 3, v77
	v_mov_b32_e32 v77, s25
	v_cmp_gt_i32_e32 vcc, s35, v96
	v_mov_b32_e32 v78, 0
	v_mov_b32_e32 v79, 0
	v_cndmask_b32_e32 v77, v233, v77, vcc
	v_add_u32_e32 v97, v77, v96
	v_cmp_gt_u32_e32 vcc, s79, v97
	v_mov_b32_e32 v77, 0
	v_mov_b32_e32 v88, 0
	v_mov_b32_e32 v89, 0
	v_mov_b32_e32 v90, 0
	v_mov_b32_e32 v91, 0
	s_and_saveexec_b64 s[40:41], vcc
	s_cbranch_execz .Lkv2_end
	v_or_b32_e32 v76, 0x8000, v97
	v_add_u32_e32 v77, s24, v97
	v_cmp_gt_u32_e32 vcc, 16, v97
	s_lshl_b32 s72, s26, 1
	s_nop 0
	v_cndmask_b32_e32 v78, v77, v76, vcc
	v_mov_b64_e32 v[76:77], s[96:97]
	v_mad_i64_i32 v[76:77], s[30:31], v78, s29, v[76:77]
	v_lshl_add_u64 v[76:77], v[76:77], 0, s[72:73]
	v_lshl_add_u64 v[76:77], v[76:77], 0, v[58:59]
	v_add_co_u32_e32 v76, vcc, 0x3000, v76
	s_nop 1
	v_addc_co_u32_e32 v77, vcc, 0, v77, vcc
	global_load_dwordx4 v[88:91], v[76:77], off
	s_nop 0
	global_load_dwordx4 v[76:79], v[76:77], off offset:512
.Lkv2_end:
	s_or_b64 exec, exec, s[40:41]
	s_mov_b64 exec, s[38:39]
	v_mad_u64_u32 v[42:43], s[30:31], v39, s71, v[36:37]
	s_waitcnt vmcnt(9)
	ds_write_b128 v42, v[12:15]
	ds_write_b128 v42, v[16:19] offset:144
	ds_write_b128 v42, v[28:31] offset:288
	v_mad_u64_u32 v[12:13], s[30:31], v40, s71, v[36:37]
	ds_write_b128 v12, v[32:35]
	v_and_b32_e32 v2, -8, v38
	s_waitcnt vmcnt(8)
	v_and_b32_e32 v12, 0xffff, v8
	v_lshrrev_b32_e32 v8, 16, v8
	v_lshl_or_b32 v12, v4, 16, v12
	v_and_b32_e32 v13, 0xffff, v24
	v_add_u32_e32 v2, v37, v2
	v_and_or_b32 v14, v4, s33, v8
	v_lshrrev_b32_e32 v4, 16, v24
	v_lshl_or_b32 v13, v20, 16, v13
	v_and_or_b32 v15, v20, s33, v4
	v_add_u32_e32 v8, 0x9800, v2
	v_and_b32_e32 v4, 0xffff, v9
	ds_write2_b64 v8, v[12:13], v[14:15] offset0:32 offset1:102
	v_lshl_or_b32 v12, v5, 16, v4
	v_and_b32_e32 v4, 0xffff, v25
	v_lshl_or_b32 v13, v21, 16, v4
	v_lshrrev_b32_e32 v4, 16, v9
	v_and_or_b32 v4, v5, s33, v4
	v_lshrrev_b32_e32 v5, 16, v25
	v_and_or_b32 v5, v21, s33, v5
	ds_write2_b64 v8, v[12:13], v[4:5] offset0:172 offset1:242
	v_and_b32_e32 v4, 0xffff, v10
	v_lshrrev_b32_e32 v8, 16, v10
	v_lshl_or_b32 v4, v6, 16, v4
	v_and_b32_e32 v5, 0xffff, v26
	v_and_or_b32 v8, v6, s33, v8
	v_lshrrev_b32_e32 v6, 16, v26
	v_lshl_or_b32 v5, v22, 16, v5
	v_and_or_b32 v9, v22, s33, v6
	v_add_u32_e32 v6, 0xa000, v2
	ds_write2_b64 v6, v[4:5], v[8:9] offset0:56 offset1:126
	v_and_b32_e32 v4, 0xffff, v11
	v_lshrrev_b32_e32 v6, 16, v11
	v_lshl_or_b32 v4, v7, 16, v4
	v_and_b32_e32 v5, 0xffff, v27
	v_and_or_b32 v6, v7, s33, v6
	v_lshrrev_b32_e32 v7, 16, v27
	v_lshl_or_b32 v5, v23, 16, v5
	v_and_or_b32 v7, v23, s33, v7
	v_add_u32_e32 v2, 0xa400, v2
	ds_write2_b64 v2, v[4:5], v[6:7] offset0:68 offset1:138
	v_cmp_gt_u32_e32 vcc, 32, v38
	s_and_b64 exec, s[38:39], vcc
	v_mad_u64_u32 v[98:99], s[30:31], v95, s71, v[36:37]
	s_waitcnt vmcnt(1)
	ds_write_b128 v98, v[68:71]
	ds_write_b128 v98, v[72:75] offset:144
	ds_write_b128 v98, v[84:87] offset:288
	v_mad_u64_u32 v[68:69], s[30:31], v96, s71, v[36:37]
	ds_write_b128 v68, v[88:91]
	v_and_b32_e32 v58, -8, v94
	s_waitcnt vmcnt(0)
	v_and_b32_e32 v68, 0xffff, v64
	v_lshrrev_b32_e32 v64, 16, v64
	v_lshl_or_b32 v68, v60, 16, v68
	v_and_b32_e32 v69, 0xffff, v80
	v_add_u32_e32 v58, v37, v58
	v_and_or_b32 v70, v60, s33, v64
	v_lshrrev_b32_e32 v60, 16, v80
	v_lshl_or_b32 v69, v76, 16, v69
	v_and_or_b32 v71, v76, s33, v60
	v_add_u32_e32 v64, 0x9800, v58
	v_and_b32_e32 v60, 0xffff, v65
	ds_write2_b64 v64, v[68:69], v[70:71] offset0:32 offset1:102
	v_lshl_or_b32 v68, v61, 16, v60
	v_and_b32_e32 v60, 0xffff, v81
	v_lshl_or_b32 v69, v77, 16, v60
	v_lshrrev_b32_e32 v60, 16, v65
	v_and_or_b32 v60, v61, s33, v60
	v_lshrrev_b32_e32 v61, 16, v81
	v_and_or_b32 v61, v77, s33, v61
	ds_write2_b64 v64, v[68:69], v[60:61] offset0:172 offset1:242
	v_and_b32_e32 v60, 0xffff, v66
	v_lshrrev_b32_e32 v64, 16, v66
	v_lshl_or_b32 v60, v62, 16, v60
	v_and_b32_e32 v61, 0xffff, v82
	v_and_or_b32 v64, v62, s33, v64
	v_lshrrev_b32_e32 v62, 16, v82
	v_lshl_or_b32 v61, v78, 16, v61
	v_and_or_b32 v65, v78, s33, v62
	v_add_u32_e32 v62, 0xa000, v58
	ds_write2_b64 v62, v[60:61], v[64:65] offset0:56 offset1:126
	v_and_b32_e32 v60, 0xffff, v67
	v_lshrrev_b32_e32 v62, 16, v67
	v_lshl_or_b32 v60, v63, 16, v60
	v_and_b32_e32 v61, 0xffff, v83
	v_and_or_b32 v62, v63, s33, v62
	v_lshrrev_b32_e32 v63, 16, v83
	v_lshl_or_b32 v61, v79, 16, v61
	v_and_or_b32 v63, v79, s33, v63
	v_add_u32_e32 v58, 0xa400, v58
	ds_write2_b64 v58, v[60:61], v[62:63] offset0:68 offset1:138
	s_branch .LBB0_409
.Lkv_other:
	v_mad_u64_u32 v[42:43], s[30:31], v39, s71, v[36:37]
	s_waitcnt vmcnt(1)
	ds_write_b128 v42, v[12:15]
	ds_write_b128 v42, v[16:19] offset:144
	ds_write_b128 v42, v[28:31] offset:288
	v_mad_u64_u32 v[12:13], s[30:31], v40, s71, v[36:37]
	ds_write_b128 v12, v[32:35]
	v_and_b32_e32 v2, -8, v38
	s_waitcnt vmcnt(0)
	v_and_b32_e32 v12, 0xffff, v8
	v_lshrrev_b32_e32 v8, 16, v8
	v_lshl_or_b32 v12, v4, 16, v12
	v_and_b32_e32 v13, 0xffff, v24
	v_add_u32_e32 v2, v37, v2
	v_and_or_b32 v14, v4, s33, v8
	v_lshrrev_b32_e32 v4, 16, v24
	v_lshl_or_b32 v13, v20, 16, v13
	v_and_or_b32 v15, v20, s33, v4
	v_add_u32_e32 v8, 0x9800, v2
	v_and_b32_e32 v4, 0xffff, v9
	ds_write2_b64 v8, v[12:13], v[14:15] offset0:32 offset1:102
	v_lshl_or_b32 v12, v5, 16, v4
	v_and_b32_e32 v4, 0xffff, v25
	v_lshl_or_b32 v13, v21, 16, v4
	v_lshrrev_b32_e32 v4, 16, v9
	v_and_or_b32 v4, v5, s33, v4
	v_lshrrev_b32_e32 v5, 16, v25
	v_and_or_b32 v5, v21, s33, v5
	ds_write2_b64 v8, v[12:13], v[4:5] offset0:172 offset1:242
	v_and_b32_e32 v4, 0xffff, v10
	v_lshrrev_b32_e32 v8, 16, v10
	v_lshl_or_b32 v4, v6, 16, v4
	v_and_b32_e32 v5, 0xffff, v26
	v_and_or_b32 v8, v6, s33, v8
	v_lshrrev_b32_e32 v6, 16, v26
	v_lshl_or_b32 v5, v22, 16, v5
	v_and_or_b32 v9, v22, s33, v6
	v_add_u32_e32 v6, 0xa000, v2
	ds_write2_b64 v6, v[4:5], v[8:9] offset0:56 offset1:126
	v_and_b32_e32 v4, 0xffff, v11
	v_lshrrev_b32_e32 v6, 16, v11
	v_lshl_or_b32 v4, v7, 16, v4
	v_and_b32_e32 v5, 0xffff, v27
	v_and_or_b32 v6, v7, s33, v6
	v_lshrrev_b32_e32 v7, 16, v27
	v_lshl_or_b32 v5, v23, 16, v5
	v_and_or_b32 v7, v23, s33, v7
	v_add_u32_e32 v2, 0xa400, v2
	ds_write2_b64 v2, v[4:5], v[6:7] offset0:68 offset1:138
